# phase-2 modulate loop rewritten by hand: 8 rows per thread in flight (loads issued together, one wait ladder, stores after)
# speedup vs baseline: 1.0074x; 1.0074x over previous
; __device__ __forceinline__ int ltid() { int t = (int)threadIdx.x; asm volatile("" : "+v"(t)); return t; }
; __device__ __forceinline__ unsigned cvt_pk_bf16(float lo, float hi) { unsigned r; asm volatile("v_cvt_pk_bf16_f32 %0, %1, %2" : "=v"(r) : "v"(lo), "v"(hi)); return r; }
; __device__ __forceinline__ void phase_modulate(const Params& p) {
;     ...
;     for (int idx = blockIdx.x * 512 + ltid(); idx < 16384 * 512; idx += gridDim.x * 512) {
;         const int m = idx >> 9, c = (idx & 511) * 4, b = m >> 12;
;         const f32x4 xv = __builtin_nontemporal_load((const f32x4*)(p.x + (size_t)m * 2048 + c)), sh = *(const f32x4*)(mods + b * 6144 + c), scl = *(const f32x4*)(mods + b * 6144 + 2048 + c);
;         u32x2 o; o[0] = cvt_pk_bf16(xv[0] * (1.f + scl[0]) + sh[0], xv[1] * (1.f + scl[1]) + sh[1]); o[1] = cvt_pk_bf16(xv[2] * (1.f + scl[2]) + sh[2], xv[3] * (1.f + scl[3]) + sh[3]);
;         *(u32x2*)(H + (size_t)m * 2048 + c) = o; }
.LBB0_163:
	s_or_b64 exec, exec, s[0:1]
	v_mov_b32_e32 v0, v170
	s_waitcnt lgkmcnt(0)
	s_barrier
	s_add_u32 s78, s90, 0xd160000
	s_mov_b32 s0, 0x800000
	v_add_u32_e32 v2, s69, v0
	s_addc_u32 s79, s91, 0
	v_cmp_gt_i32_e32 vcc, s0, v2
	s_and_saveexec_b64 s[0:1], vcc
	v_readlane_b32 s44, v241, 18
	v_readlane_b32 s45, v241, 19
	v_readlane_b32 s46, v241, 20
	v_readlane_b32 s47, v241, 21
	v_readlane_b32 s48, v241, 22
	v_readlane_b32 s49, v241, 23
	v_readlane_b32 s50, v241, 24
	v_readlane_b32 s51, v241, 25
	v_readlane_b32 s52, v241, 26
	v_readlane_b32 s53, v241, 27
	v_readlane_b32 s54, v241, 28
	v_readlane_b32 s55, v241, 29
	v_readlane_b32 s56, v241, 30
	v_readlane_b32 s57, v241, 31
	v_readlane_b32 s58, v241, 32
	v_readlane_b32 s59, v241, 33
	s_cbranch_execz .LBB0_166
	s_mov_b64 s[36:37], s[44:45]
	v_lshlrev_b32_e32 v36, 4, v0
	v_mov_b32_e32 v37, 0
	v_lshlrev_b32_e32 v38, 3, v0
	v_mov_b32_e32 v39, 0
	v_ashrrev_i32_e32 v16, 9, v2
	v_mov_b32_e32 v17, 0
	v_lshlrev_b64 v[40:41], 13, v[16:17]
	v_lshl_add_u64 v[40:41], s[44:45], 0, v[40:41]
	v_lshl_add_u64 v[40:41], v[40:41], 0, v[36:37]
	v_lshlrev_b64 v[42:43], 12, v[16:17]
	v_lshl_add_u64 v[42:43], s[78:79], 0, v[42:43]
	v_lshl_add_u64 v[42:43], v[42:43], 0, v[38:39]
	s_movk_i32 s2, 0x2000
	s_mov_b32 s3, 0
	s_lshl_b32 s4, s33, 13
	s_mov_b32 s5, 0
	s_lshl_b32 s6, s33, 12
	s_mov_b32 s7, 0
	s_lshl_b32 s8, s33, 3
	s_lshl_b32 s9, s40, 3
.Lmod_group:
	v_ashrrev_i32_e32 v44, 12, v16
	v_mul_u32_u24_e32 v44, 0x6000, v44
	v_add_u32_e32 v44, v44, v36
	v_mov_b32_e32 v45, 0
	v_lshl_add_u64 v[44:45], s[70:71], 0, v[44:45]
	v_lshl_add_u64 v[46:47], v[44:45], 0, s[2:3]
	global_load_dwordx4 v[50:53], v[44:45], off
	global_load_dwordx4 v[54:57], v[46:47], off
	global_load_dwordx4 v[60:63], v[40:41], off nt
	v_lshl_add_u64 v[48:49], v[40:41], 0, s[4:5]
	global_load_dwordx4 v[64:67], v[48:49], off nt
	v_lshl_add_u64 v[48:49], v[48:49], 0, s[4:5]
	global_load_dwordx4 v[68:71], v[48:49], off nt
	v_lshl_add_u64 v[48:49], v[48:49], 0, s[4:5]
	global_load_dwordx4 v[72:75], v[48:49], off nt
	v_lshl_add_u64 v[48:49], v[48:49], 0, s[4:5]
	global_load_dwordx4 v[76:79], v[48:49], off nt
	v_lshl_add_u64 v[48:49], v[48:49], 0, s[4:5]
	global_load_dwordx4 v[80:83], v[48:49], off nt
	v_lshl_add_u64 v[48:49], v[48:49], 0, s[4:5]
	global_load_dwordx4 v[84:87], v[48:49], off nt
	v_lshl_add_u64 v[48:49], v[48:49], 0, s[4:5]
	global_load_dwordx4 v[88:91], v[48:49], off nt
	v_lshl_add_u64 v[40:41], v[48:49], 0, s[4:5]
	s_waitcnt vmcnt(8)
	v_add_f32_e32 v54, 1.0, v54
	v_add_f32_e32 v55, 1.0, v55
	v_add_f32_e32 v56, 1.0, v56
	v_add_f32_e32 v57, 1.0, v57
	s_waitcnt vmcnt(7)
	v_fma_f32 v60, v60, v54, v50
	v_fma_f32 v61, v61, v55, v51
	v_fma_f32 v62, v62, v56, v52
	v_fma_f32 v63, v63, v57, v53
	v_cvt_pk_bf16_f32 v60, v60, v61
	v_cvt_pk_bf16_f32 v61, v62, v63
	s_waitcnt vmcnt(6)
	v_fma_f32 v64, v64, v54, v50
	v_fma_f32 v65, v65, v55, v51
	v_fma_f32 v66, v66, v56, v52
	v_fma_f32 v67, v67, v57, v53
	v_cvt_pk_bf16_f32 v64, v64, v65
	v_cvt_pk_bf16_f32 v65, v66, v67
	s_waitcnt vmcnt(5)
	v_fma_f32 v68, v68, v54, v50
	v_fma_f32 v69, v69, v55, v51
	v_fma_f32 v70, v70, v56, v52
	v_fma_f32 v71, v71, v57, v53
	v_cvt_pk_bf16_f32 v68, v68, v69
	v_cvt_pk_bf16_f32 v69, v70, v71
	s_waitcnt vmcnt(4)
	v_fma_f32 v72, v72, v54, v50
	v_fma_f32 v73, v73, v55, v51
	v_fma_f32 v74, v74, v56, v52
	v_fma_f32 v75, v75, v57, v53
	v_cvt_pk_bf16_f32 v72, v72, v73
	v_cvt_pk_bf16_f32 v73, v74, v75
	s_waitcnt vmcnt(3)
	v_fma_f32 v76, v76, v54, v50
	v_fma_f32 v77, v77, v55, v51
	v_fma_f32 v78, v78, v56, v52
	v_fma_f32 v79, v79, v57, v53
	v_cvt_pk_bf16_f32 v76, v76, v77
	v_cvt_pk_bf16_f32 v77, v78, v79
	s_waitcnt vmcnt(2)
	v_fma_f32 v80, v80, v54, v50
	v_fma_f32 v81, v81, v55, v51
	v_fma_f32 v82, v82, v56, v52
	v_fma_f32 v83, v83, v57, v53
	v_cvt_pk_bf16_f32 v80, v80, v81
	v_cvt_pk_bf16_f32 v81, v82, v83
	s_waitcnt vmcnt(1)
	v_fma_f32 v84, v84, v54, v50
	v_fma_f32 v85, v85, v55, v51
	v_fma_f32 v86, v86, v56, v52
	v_fma_f32 v87, v87, v57, v53
	v_cvt_pk_bf16_f32 v84, v84, v85
	v_cvt_pk_bf16_f32 v85, v86, v87
	s_waitcnt vmcnt(0)
	v_fma_f32 v88, v88, v54, v50
	v_fma_f32 v89, v89, v55, v51
	v_fma_f32 v90, v90, v56, v52
	v_fma_f32 v91, v91, v57, v53
	v_cvt_pk_bf16_f32 v88, v88, v89
	v_cvt_pk_bf16_f32 v89, v90, v91
	global_store_dwordx2 v[42:43], v[60:61], off
	v_lshl_add_u64 v[42:43], v[42:43], 0, s[6:7]
	global_store_dwordx2 v[42:43], v[64:65], off
	v_lshl_add_u64 v[42:43], v[42:43], 0, s[6:7]
	global_store_dwordx2 v[42:43], v[68:69], off
	v_lshl_add_u64 v[42:43], v[42:43], 0, s[6:7]
	global_store_dwordx2 v[42:43], v[72:73], off
	v_lshl_add_u64 v[42:43], v[42:43], 0, s[6:7]
	global_store_dwordx2 v[42:43], v[76:77], off
	v_lshl_add_u64 v[42:43], v[42:43], 0, s[6:7]
	global_store_dwordx2 v[42:43], v[80:81], off
	v_lshl_add_u64 v[42:43], v[42:43], 0, s[6:7]
	global_store_dwordx2 v[42:43], v[84:85], off
	v_lshl_add_u64 v[42:43], v[42:43], 0, s[6:7]
	global_store_dwordx2 v[42:43], v[88:89], off
	v_lshl_add_u64 v[42:43], v[42:43], 0, s[6:7]
	v_add_u32_e32 v16, s8, v16
	v_add_u32_e32 v2, s9, v2
	v_cmp_gt_i32_e32 vcc, 0x800000, v2
	s_cbranch_vccnz .Lmod_group
